# PRE S0: lora-weight fragment loads spread through the stage instead of one burst at its head; S0 store-drain waits removed (mode A)
# speedup vs baseline: 1.0092x; 1.0092x over previous
.LBB0_81:
	v_mov_b32_e32 v1, v180
	v_mov_b32_e32 v48, v180
	v_add_lshl_u32 v240, s77, v1, 4
	v_add_lshl_u32 v241, s67, v1, 4
	v_add_lshl_u32 v242, s94, v1, 4
	v_add_lshl_u32 v243, s95, v1, 4
	s_nop 0
	v_lshlrev_b32_e32 v45, 16, v104
	v_and_b32_e32 v49, 7, v48
	v_lshlrev_b32_e32 v50, 5, v49
	v_add_u32_e32 v51, 0, v50
	v_add_u32_e32 v2, 0x25400, v51
	v_add_u32_e32 v3, 0x25600, v51
	ds_read_b128 v[28:31], v2
	ds_read_b128 v[32:35], v2 offset:16
	ds_read_b128 v[36:39], v3
	ds_read_b128 v[40:43], v3 offset:16
	v_lshlrev_b32_e32 v2, 16, v100
	v_lshlrev_b32_e32 v44, 16, v108
	v_pk_add_f32 v[44:45], v[44:45], v[2:3] op_sel_hi:[1,0] neg_lo:[0,1] neg_hi:[0,1]
	s_waitcnt lgkmcnt(3)
	global_load_dwordx4 v[20:23], v240, s[54:55]
	v_mov_b32_e32 v46, v28
	s_waitcnt lgkmcnt(1)
	v_mov_b32_e32 v47, v36
	v_pk_mul_f32 v[44:45], v[44:45], v[46:47]
	v_mov_b32_e32 v36, v29
	v_add_f32_e32 v2, v44, v2
	v_add_f32_e32 v3, v2, v45
	v_and_b32_e32 v2, 0xffff0000, v100
	v_and_b32_e32 v45, 0xffff0000, v104
	v_and_b32_e32 v44, 0xffff0000, v108
	v_pk_add_f32 v[44:45], v[44:45], v[2:3] op_sel_hi:[1,0] neg_lo:[0,1] neg_hi:[0,1]
	v_add_u32_e32 v1, s42, v48
	v_pk_mul_f32 v[28:29], v[44:45], v[36:37]
	v_mov_b32_e32 v36, v30
	v_add_f32_e32 v2, v28, v2
	v_add_f32_e32 v44, v2, v29
	v_lshlrev_b32_e32 v2, 16, v101
	v_lshlrev_b32_e32 v29, 16, v105
	v_lshlrev_b32_e32 v28, 16, v109
	v_pk_add_f32 v[28:29], v[28:29], v[2:3] op_sel_hi:[1,0] neg_lo:[0,1] neg_hi:[0,1]
	v_mov_b32_e32 v37, v38
	v_pk_mul_f32 v[28:29], v[28:29], v[36:37]
	v_mov_b32_e32 v38, v31
	v_add_f32_e32 v2, v28, v2
	v_add_f32_e32 v36, v2, v29
	v_and_b32_e32 v2, 0xffff0000, v101
	v_and_b32_e32 v29, 0xffff0000, v105
	v_and_b32_e32 v28, 0xffff0000, v109
	v_pk_add_f32 v[28:29], v[28:29], v[2:3] op_sel_hi:[1,0] neg_lo:[0,1] neg_hi:[0,1]
	v_mov_b32_e32 v30, v32
	v_pk_mul_f32 v[28:29], v[28:29], v[38:39]
	s_waitcnt lgkmcnt(0)
	v_mov_b32_e32 v31, v40
	v_add_f32_e32 v2, v28, v2
	v_add_f32_e32 v37, v2, v29
	v_lshlrev_b32_e32 v2, 16, v102
	v_lshlrev_b32_e32 v29, 16, v106
	v_lshlrev_b32_e32 v28, 16, v110
	v_pk_add_f32 v[28:29], v[28:29], v[2:3] op_sel_hi:[1,0] neg_lo:[0,1] neg_hi:[0,1]
	v_mov_b32_e32 v40, v33
	v_pk_mul_f32 v[28:29], v[28:29], v[30:31]
	v_mov_b32_e32 v30, v34
	v_add_f32_e32 v2, v28, v2
	v_add_f32_e32 v32, v2, v29
	v_and_b32_e32 v2, 0xffff0000, v102
	global_load_dwordx4 v[24:27], v240, s[58:59]
	v_and_b32_e32 v29, 0xffff0000, v106
	v_and_b32_e32 v28, 0xffff0000, v110
	v_pk_add_f32 v[28:29], v[28:29], v[2:3] op_sel_hi:[1,0] neg_lo:[0,1] neg_hi:[0,1]
	v_mov_b32_e32 v31, v42
	v_pk_mul_f32 v[28:29], v[28:29], v[40:41]
	v_mov_b32_e32 v42, v35
	v_add_f32_e32 v2, v28, v2
	v_add_f32_e32 v33, v2, v29
	v_lshlrev_b32_e32 v2, 16, v103
	v_lshlrev_b32_e32 v29, 16, v107
	v_lshlrev_b32_e32 v28, 16, v111
	v_pk_add_f32 v[28:29], v[28:29], v[2:3] op_sel_hi:[1,0] neg_lo:[0,1] neg_hi:[0,1]
	v_ashrrev_i32_e32 v1, 3, v1
	v_pk_mul_f32 v[28:29], v[28:29], v[30:31]
	v_add_f32_e32 v30, v44, v44
	v_add_f32_e32 v2, v28, v2
	v_add_f32_e32 v34, v2, v29
	v_and_b32_e32 v2, 0xffff0000, v103
	v_and_b32_e32 v29, 0xffff0000, v107
	v_and_b32_e32 v28, 0xffff0000, v111
	v_pk_add_f32 v[28:29], v[28:29], v[2:3] op_sel_hi:[1,0] neg_lo:[0,1] neg_hi:[0,1]
	v_add_f32_e32 v3, v3, v3
	v_mul_f32_e32 v3, 0x3fb8aa3b, v3
	v_exp_f32_e32 v3, v3
	v_mul_f32_e32 v30, 0x3fb8aa3b, v30
	v_exp_f32_e32 v31, v30
	v_pk_mul_f32 v[28:29], v[28:29], v[42:43]
	v_add_f32_e32 v3, 1.0, v3
	v_rcp_f32_e32 v30, v3
	v_add_f32_e32 v3, 1.0, v31
	v_rcp_f32_e32 v31, v3
	v_add_f32_e32 v2, v28, v2
	v_add_f32_e32 v28, v36, v36
	v_mul_f32_e32 v28, 0x3fb8aa3b, v28
	v_add_f32_e32 v29, v2, v29
	v_pk_fma_f32 v[2:3], v[30:31], 2.0, 1.0 op_sel_hi:[1,0,0] neg_lo:[1,0,0] neg_hi:[1,0,0]
	v_exp_f32_e32 v30, v28
	v_add_f32_e32 v28, v37, v37
	v_mul_f32_e32 v28, 0x3fb8aa3b, v28
	v_exp_f32_e32 v31, v28
	v_cvt_pk_bf16_f32 v28, v2, v3
	v_add_f32_e32 v2, 1.0, v30
	v_add_f32_e32 v30, v32, v32
	v_add_f32_e32 v3, 1.0, v31
	v_add_f32_e32 v31, v33, v33
	global_load_dwordx4 v[60:63], v241, s[54:55]
	v_mul_f32_e32 v30, 0x3fb8aa3b, v30
	v_mul_f32_e32 v31, 0x3fb8aa3b, v31
	v_add_f32_e32 v32, v34, v34
	v_add_f32_e32 v29, v29, v29
	v_exp_f32_e32 v30, v30
	v_exp_f32_e32 v31, v31
	v_mul_f32_e32 v32, 0x3fb8aa3b, v32
	v_mul_f32_e32 v29, 0x3fb8aa3b, v29
	v_exp_f32_e32 v32, v32
	v_exp_f32_e32 v29, v29
	v_rcp_f32_e32 v2, v2
	v_rcp_f32_e32 v3, v3
	v_add_f32_e32 v30, 1.0, v30
	v_add_f32_e32 v31, 1.0, v31
	v_rcp_f32_e32 v30, v30
	v_rcp_f32_e32 v31, v31
	v_add_f32_e32 v32, 1.0, v32
	v_add_f32_e32 v29, 1.0, v29
	v_rcp_f32_e32 v32, v32
	v_rcp_f32_e32 v33, v29
	v_pk_fma_f32 v[2:3], v[2:3], 2.0, 1.0 op_sel_hi:[1,0,0] neg_lo:[1,0,0] neg_hi:[1,0,0]
	v_mul_lo_u32 v76, v1, s64
	v_cvt_pk_bf16_f32 v29, v2, v3
	v_pk_fma_f32 v[2:3], v[30:31], 2.0, 1.0 op_sel_hi:[1,0,0] neg_lo:[1,0,0] neg_hi:[1,0,0]
	v_lshlrev_b32_e32 v77, 4, v49
	v_cvt_pk_bf16_f32 v30, v2, v3
	v_pk_fma_f32 v[2:3], v[32:33], 2.0, 1.0 op_sel_hi:[1,0,0] neg_lo:[1,0,0] neg_hi:[1,0,0]
	v_readlane_b32 s27, v253, 61
	v_cvt_pk_bf16_f32 v31, v2, v3
	v_add_u32_e32 v3, 0x25700, v51
	v_add3_u32 v2, s27, v76, v77
	ds_write_b128 v2, v[28:31]
	v_add_u32_e32 v2, 0x25500, v51
	global_load_dwordx4 v[56:59], v241, s[58:59]
	ds_read_b128 v[28:31], v2
	ds_read_b128 v[32:35], v2 offset:16
	ds_read_b128 v[36:39], v3
	ds_read_b128 v[40:43], v3 offset:16
	s_nop 0
	v_lshlrev_b32_e32 v2, 16, v112
	v_and_b32_e32 v3, 0xffff0000, v112
	v_lshlrev_b32_e32 v44, 16, v116
	v_and_b32_e32 v45, 0xffff0000, v116
	v_lshlrev_b32_e32 v46, 16, v120
	v_and_b32_e32 v47, 0xffff0000, v120
	v_pk_add_f32 v[44:45], v[44:45], v[2:3] neg_lo:[0,1] neg_hi:[0,1]
	v_readlane_b32 s27, v253, 62
	s_waitcnt lgkmcnt(3)
	v_pk_fma_f32 v[28:29], v[44:45], v[28:29], v[2:3]
	v_pk_add_f32 v[2:3], v[46:47], v[2:3] neg_lo:[0,1] neg_hi:[0,1]
	v_lshlrev_b32_e32 v44, 16, v121
	s_waitcnt lgkmcnt(1)
	v_pk_fma_f32 v[2:3], v[2:3], v[36:37], v[28:29]
	v_lshlrev_b32_e32 v28, 16, v113
	v_and_b32_e32 v29, 0xffff0000, v113
	v_lshlrev_b32_e32 v36, 16, v117
	v_and_b32_e32 v37, 0xffff0000, v117
	v_and_b32_e32 v45, 0xffff0000, v121
	v_pk_add_f32 v[36:37], v[36:37], v[28:29] neg_lo:[0,1] neg_hi:[0,1]
	s_nop 0
	v_lshlrev_b32_e32 v46, 16, v144
	v_pk_fma_f32 v[30:31], v[36:37], v[30:31], v[28:29]
	v_pk_add_f32 v[28:29], v[44:45], v[28:29] neg_lo:[0,1] neg_hi:[0,1]
	v_lshlrev_b32_e32 v36, 16, v118
	v_pk_fma_f32 v[30:31], v[28:29], v[38:39], v[30:31]
	v_lshlrev_b32_e32 v28, 16, v114
	global_load_dwordx4 v[72:75], v242, s[54:55]
	v_and_b32_e32 v29, 0xffff0000, v114
	v_and_b32_e32 v37, 0xffff0000, v118
	v_lshlrev_b32_e32 v38, 16, v122
	v_and_b32_e32 v39, 0xffff0000, v122
	v_pk_add_f32 v[36:37], v[36:37], v[28:29] neg_lo:[0,1] neg_hi:[0,1]
	v_lshlrev_b32_e32 v44, 16, v140
	v_pk_fma_f32 v[32:33], v[36:37], v[32:33], v[28:29]
	v_pk_add_f32 v[28:29], v[38:39], v[28:29] neg_lo:[0,1] neg_hi:[0,1]
	v_lshlrev_b32_e32 v36, 16, v119
	v_and_b32_e32 v37, 0xffff0000, v119
	v_lshlrev_b32_e32 v38, 16, v115
	v_and_b32_e32 v39, 0xffff0000, v115
	s_waitcnt lgkmcnt(0)
	v_pk_fma_f32 v[32:33], v[28:29], v[40:41], v[32:33]
	v_lshlrev_b32_e32 v28, 16, v123
	v_and_b32_e32 v29, 0xffff0000, v123
	v_pk_add_f32 v[36:37], v[36:37], v[38:39] neg_lo:[0,1] neg_hi:[0,1]
	v_pk_add_f32 v[28:29], v[28:29], v[38:39] neg_lo:[0,1] neg_hi:[0,1]
	v_pk_fma_f32 v[34:35], v[36:37], v[34:35], v[38:39]
	v_and_b32_e32 v45, 0xffff0000, v140
	v_pk_fma_f32 v[34:35], v[28:29], v[42:43], v[34:35]
	v_cvt_pk_bf16_f32 v28, v2, v3
	v_cvt_pk_bf16_f32 v29, v30, v31
	v_cvt_pk_bf16_f32 v30, v32, v33
	v_cvt_pk_bf16_f32 v31, v34, v35
	v_add3_u32 v2, s27, v76, v77
	ds_write_b128 v2, v[28:31]
	v_add_u32_e32 v2, 0x24e00, v51
	v_add_u32_e32 v3, 0x24f00, v51
	ds_read_b128 v[28:31], v2
	ds_read_b128 v[32:35], v2 offset:16
	ds_read_b128 v[36:39], v3
	ds_read_b128 v[40:43], v3 offset:16
	v_lshlrev_b32_e32 v2, 16, v136
	v_and_b32_e32 v3, 0xffff0000, v136
	v_and_b32_e32 v47, 0xffff0000, v144
	v_pk_add_f32 v[44:45], v[44:45], v[2:3] neg_lo:[0,1] neg_hi:[0,1]
	v_cmp_gt_i32_e32 vcc, 32, v1
	s_waitcnt lgkmcnt(3)
	v_pk_fma_f32 v[28:29], v[44:45], v[28:29], v[2:3]
	v_pk_add_f32 v[2:3], v[46:47], v[2:3] neg_lo:[0,1] neg_hi:[0,1]
	v_lshlrev_b32_e32 v44, 16, v145
	s_waitcnt lgkmcnt(1)
	v_pk_fma_f32 v[28:29], v[2:3], v[36:37], v[28:29]
	v_lshlrev_b32_e32 v2, 16, v137
	global_load_dwordx4 v[64:67], v242, s[58:59]
	v_and_b32_e32 v3, 0xffff0000, v137
	v_lshlrev_b32_e32 v36, 16, v141
	v_and_b32_e32 v37, 0xffff0000, v141
	v_and_b32_e32 v45, 0xffff0000, v145
	v_pk_add_f32 v[36:37], v[36:37], v[2:3] neg_lo:[0,1] neg_hi:[0,1]
	v_lshlrev_b32_e32 v46, 16, v132
	v_pk_fma_f32 v[30:31], v[36:37], v[30:31], v[2:3]
	v_pk_add_f32 v[2:3], v[44:45], v[2:3] neg_lo:[0,1] neg_hi:[0,1]
	v_lshlrev_b32_e32 v36, 16, v142
	v_pk_fma_f32 v[30:31], v[2:3], v[38:39], v[30:31]
	v_lshlrev_b32_e32 v2, 16, v138
	v_and_b32_e32 v3, 0xffff0000, v138
	v_and_b32_e32 v37, 0xffff0000, v142
	v_lshlrev_b32_e32 v38, 16, v146
	v_and_b32_e32 v39, 0xffff0000, v146
	v_pk_add_f32 v[36:37], v[36:37], v[2:3] neg_lo:[0,1] neg_hi:[0,1]
	v_lshlrev_b32_e32 v44, 16, v128
	v_pk_fma_f32 v[32:33], v[36:37], v[32:33], v[2:3]
	v_pk_add_f32 v[2:3], v[38:39], v[2:3] neg_lo:[0,1] neg_hi:[0,1]
	v_lshlrev_b32_e32 v36, 16, v143
	v_and_b32_e32 v37, 0xffff0000, v143
	v_lshlrev_b32_e32 v38, 16, v139
	v_and_b32_e32 v39, 0xffff0000, v139
	s_waitcnt lgkmcnt(0)
	v_pk_fma_f32 v[32:33], v[2:3], v[40:41], v[32:33]
	v_lshlrev_b32_e32 v2, 16, v147
	v_and_b32_e32 v3, 0xffff0000, v147
	v_pk_add_f32 v[36:37], v[36:37], v[38:39] neg_lo:[0,1] neg_hi:[0,1]
	v_pk_add_f32 v[2:3], v[2:3], v[38:39] neg_lo:[0,1] neg_hi:[0,1]
	v_pk_fma_f32 v[34:35], v[36:37], v[34:35], v[38:39]
	v_and_b32_e32 v45, 0xffff0000, v128
	v_pk_fma_f32 v[34:35], v[2:3], v[42:43], v[34:35]
	v_mov_b32_e32 v2, 0x1d400
	v_mov_b32_e32 v3, 0xd800
	v_cndmask_b32_e32 v2, v2, v3, vcc
	v_lshlrev_b32_e32 v3, 8, v1
	v_add_u32_e32 v2, 0, v2
	v_and_b32_e32 v3, 0x1f00, v3
	v_add3_u32 v2, v2, v3, v50
	ds_write_b128 v2, v[28:31]
	ds_write_b128 v2, v[32:35] offset:16
	v_add_u32_e32 v2, 0x25000, v51
	v_add_u32_e32 v3, 0x25100, v51
	ds_read_b128 v[28:31], v2
	ds_read_b128 v[32:35], v2 offset:16
	global_load_dwordx4 v[68:71], v243, s[54:55]
	ds_read_b128 v[36:39], v3
	ds_read_b128 v[40:43], v3 offset:16
	v_lshlrev_b32_e32 v2, 16, v124
	v_and_b32_e32 v3, 0xffff0000, v124
	v_and_b32_e32 v47, 0xffff0000, v132
	v_pk_add_f32 v[44:45], v[44:45], v[2:3] neg_lo:[0,1] neg_hi:[0,1]
	v_cmp_eq_u32_e32 vcc, 0, v49
	s_waitcnt lgkmcnt(3)
	v_pk_fma_f32 v[28:29], v[44:45], v[28:29], v[2:3]
	v_pk_add_f32 v[2:3], v[46:47], v[2:3] neg_lo:[0,1] neg_hi:[0,1]
	s_waitcnt lgkmcnt(1)
	v_pk_fma_f32 v[76:77], v[2:3], v[36:37], v[28:29]
	v_lshlrev_b32_e32 v2, 16, v125
	v_and_b32_e32 v3, 0xffff0000, v125
	v_lshlrev_b32_e32 v28, 16, v129
	v_and_b32_e32 v29, 0xffff0000, v129
	v_lshlrev_b32_e32 v36, 16, v133
	v_and_b32_e32 v37, 0xffff0000, v133
	v_pk_add_f32 v[28:29], v[28:29], v[2:3] neg_lo:[0,1] neg_hi:[0,1]
	s_nop 0
	v_pk_fma_f32 v[28:29], v[28:29], v[30:31], v[2:3]
	v_pk_add_f32 v[2:3], v[36:37], v[2:3] neg_lo:[0,1] neg_hi:[0,1]
	v_lshlrev_b32_e32 v30, 16, v134
	v_pk_fma_f32 v[78:79], v[2:3], v[38:39], v[28:29]
	v_lshlrev_b32_e32 v2, 16, v126
	v_and_b32_e32 v3, 0xffff0000, v126
	v_lshlrev_b32_e32 v28, 16, v130
	v_and_b32_e32 v29, 0xffff0000, v130
	v_and_b32_e32 v31, 0xffff0000, v134
	v_pk_add_f32 v[28:29], v[28:29], v[2:3] neg_lo:[0,1] neg_hi:[0,1]
	v_add_u32_e32 v38, 0x24700, v51
	v_pk_fma_f32 v[28:29], v[28:29], v[32:33], v[2:3]
	v_pk_add_f32 v[2:3], v[30:31], v[2:3] neg_lo:[0,1] neg_hi:[0,1]
	v_lshlrev_b32_e32 v32, 16, v127
	s_waitcnt lgkmcnt(0)
	v_pk_fma_f32 v[80:81], v[2:3], v[40:41], v[28:29]
	v_lshlrev_b32_e32 v28, 16, v131
	v_and_b32_e32 v29, 0xffff0000, v131
	v_and_b32_e32 v33, 0xffff0000, v127
	v_pk_add_f32 v[36:37], v[28:29], v[32:33] neg_lo:[0,1] neg_hi:[0,1]
	ds_read_b128 v[28:31], v38
	v_lshlrev_b32_e32 v2, 16, v135
	v_and_b32_e32 v3, 0xffff0000, v135
	v_pk_fma_f32 v[34:35], v[36:37], v[34:35], v[32:33]
	v_pk_add_f32 v[2:3], v[2:3], v[32:33] neg_lo:[0,1] neg_hi:[0,1]
	global_load_dwordx4 v[52:55], v243, s[58:59]
	s_nop 0
	v_pk_fma_f32 v[82:83], v[2:3], v[42:43], v[34:35]
	ds_read_b128 v[32:35], v38 offset:16
	s_waitcnt lgkmcnt(1)
	v_mul_f32_e32 v3, v77, v29
	v_mul_f32_e32 v2, v76, v28
	v_mul_f32_e32 v3, v3, v3
	v_fmac_f32_e32 v3, v2, v2
	v_mul_f32_e32 v2, v78, v30
	v_fmac_f32_e32 v3, v2, v2
	v_mul_f32_e32 v2, v79, v31
	v_fmac_f32_e32 v3, v2, v2
	s_waitcnt lgkmcnt(0)
	v_mul_f32_e32 v2, v80, v32
	v_fmac_f32_e32 v3, v2, v2
	v_mul_f32_e32 v2, v81, v33
	v_fmac_f32_e32 v3, v2, v2
	v_mul_f32_e32 v2, v82, v34
	v_fmac_f32_e32 v3, v2, v2
	v_mul_f32_e32 v2, v83, v35
	v_lshlrev_b32_e32 v28, 2, v48
	v_fmac_f32_e32 v3, v2, v2
	v_xor_b32_e32 v2, 4, v28
	ds_bpermute_b32 v2, v2, v3
	s_waitcnt lgkmcnt(0)
	v_add_f32_e32 v2, v3, v2
	v_xor_b32_e32 v3, 8, v28
	ds_bpermute_b32 v3, v3, v2
	s_waitcnt lgkmcnt(0)
	v_add_f32_e32 v2, v2, v3
	v_xor_b32_e32 v3, 16, v28
	ds_bpermute_b32 v3, v3, v2
	s_and_saveexec_b64 s[30:31], vcc
	s_cbranch_execz .LBB0_83
	s_waitcnt lgkmcnt(0)
	v_add_f32_e32 v2, v2, v3
	v_add_f32_e32 v2, 0x2b8cbccc, v2
	s_mov_b32 s27, 0xf800000
	v_mul_f32_e32 v3, 0x4f800000, v2
	v_cmp_gt_f32_e32 vcc, s27, v2
	v_lshl_add_u32 v1, v1, 2, 0
	v_add_u32_e32 v1, 0x24000, v1
	v_cndmask_b32_e32 v2, v2, v3, vcc
	v_sqrt_f32_e32 v3, v2
	s_nop 0
	v_add_u32_e32 v28, -1, v3
	v_fma_f32 v30, -v28, v3, v2
	v_add_u32_e32 v29, 1, v3
	v_cmp_ge_f32_e64 s[38:39], 0, v30
	s_nop 1
	v_cndmask_b32_e64 v28, v3, v28, s[38:39]
	v_fma_f32 v3, -v29, v3, v2
	v_cmp_lt_f32_e64 s[38:39], 0, v3
	s_nop 1
	v_cndmask_b32_e64 v3, v28, v29, s[38:39]
	v_mul_f32_e32 v28, 0x37800000, v3
	v_cndmask_b32_e32 v3, v3, v28, vcc
	v_cmp_class_f32_e32 vcc, v2, v222
	s_nop 1
	v_cndmask_b32_e32 v2, v3, v2, vcc
	v_div_scale_f32 v3, s[38:39], v2, v2, 1.0
	v_rcp_f32_e32 v28, v3
	s_nop 0
	v_fma_f32 v29, -v3, v28, 1.0
	v_fmac_f32_e32 v28, v29, v28
	v_div_scale_f32 v29, vcc, 1.0, v2, 1.0
	v_mul_f32_e32 v30, v29, v28
	v_fma_f32 v31, -v3, v30, v29
	v_fmac_f32_e32 v30, v31, v28
	v_fma_f32 v3, -v3, v30, v29
	v_div_fmas_f32 v3, v3, v28, v30
	v_div_fixup_f32 v2, v3, v2, 1.0
	ds_write_b32 v1, v2
